# stacked + strategy 7 instruction selection: canonicalize+max triples folded into one v_max in the attention softmax
# baseline (speedup 1.0000x reference)
.LBB0_198:
	v_lshlrev_b32_e32 v180, 2, v32
	v_and_b32_e32 v34, 63, v86
	v_or_b32_e32 v87, 0x70, v180
	s_cmp_lt_u32 s24, 32
	v_lshlrev_b32_e32 v32, 2, v34
	v_cmp_le_i32_e64 s[4:5], v87, v85
	v_or_b32_e32 v34, 0x71, v180
	s_cselect_b64 s[14:15], -1, 0
	v_cmp_le_i32_e64 s[6:7], v34, v85
	v_or_b32_e32 v34, 0x72, v180
	v_mov_b32_e32 v72, 0xf149f2ca
	s_or_b64 vcc, s[14:15], s[4:5]
	v_cmp_le_i32_e64 s[8:9], v34, v85
	v_or_b32_e32 v34, 0x73, v180
	v_cndmask_b32_e32 v127, v72, v64, vcc
	s_or_b64 vcc, s[14:15], s[6:7]
	v_cmp_le_i32_e64 s[10:11], v34, v85
	v_cndmask_b32_e32 v130, v72, v65, vcc
	s_or_b64 vcc, s[14:15], s[8:9]
	v_cndmask_b32_e32 v131, v72, v66, vcc
	s_or_b64 vcc, s[14:15], s[10:11]
	v_cndmask_b32_e32 v101, v72, v67, vcc
	v_max_f32_e32 v34, v127, v130
	v_max_f32_e32 v35, v101, v101
	v_max_f32_e32 v64, v131, v131
	v_max_f32_e32 v35, v64, v35
	v_xor_b32_e32 v198, 64, v32
	v_max3_f32 v34, v34, v35, v72
	ds_bpermute_b32 v35, v198, v34
	v_xor_b32_e32 v199, 0x80, v32
	s_and_b64 vcc, exec, s[12:13]
	s_waitcnt lgkmcnt(0)
	v_max_f32_e32 v32, v35, v35
	v_max_f32_e32 v73, v34, v32
	ds_bpermute_b32 v74, v199, v73
	s_cbranch_vccnz .LBB0_200
	v_max_f32_e32 v24, v68, v69
	v_max_f32_e32 v25, v70, v71
	s_mov_b32 s3, 0xf149f2ca
	v_max3_f32 v24, v24, v25, s3
	ds_bpermute_b32 v25, v198, v24
	s_waitcnt lgkmcnt(0)
	v_max_f32_e32 v25, v25, v25
	v_max_f32_e32 v24, v24, v25
	ds_bpermute_b32 v25, v199, v24
	s_waitcnt lgkmcnt(0)
	v_max3_f32 v201, v24, v25, s3
	v_mul_f32_e32 v25, 0xbfb8aa3b, v201
	v_fmamk_f32 v26, v235, 0xf149f2ca, v25
	v_exp_f32_e32 v56, v26
	v_fmamk_f32 v27, v68, 0x3fb8aa3b, v25
	v_exp_f32_e32 v68, v27
	v_fmamk_f32 v28, v69, 0x3fb8aa3b, v25
	v_add_f32_e32 v27, 0, v56
	v_add_f32_e32 v27, v56, v27
	v_add_f32_e32 v27, v56, v27
	v_add_f32_e32 v27, v56, v27
	v_add_f32_e32 v27, v56, v27
	v_add_f32_e32 v27, v56, v27
	v_add_f32_e32 v27, v56, v27
	v_add_f32_e32 v27, v56, v27
	v_add_f32_e32 v27, v56, v27
	v_add_f32_e32 v27, v56, v27
	v_add_f32_e32 v27, v56, v27
	v_add_f32_e32 v27, v56, v27
	v_add_f32_e32 v27, v56, v27
	v_add_f32_e32 v27, v56, v27
	v_add_f32_e32 v27, v56, v27
	v_add_f32_e32 v27, v56, v27
	v_add_f32_e32 v27, v56, v27
	v_add_f32_e32 v27, v56, v27
	v_add_f32_e32 v27, v56, v27
	v_add_f32_e32 v27, v56, v27
	v_add_f32_e32 v27, v56, v27
	v_add_f32_e32 v27, v56, v27
	v_add_f32_e32 v27, v56, v27
	v_add_f32_e32 v27, v56, v27
	v_add_f32_e32 v27, v56, v27
	v_sub_f32_e32 v24, 0xf149f2ca, v201
	v_fmamk_f32 v26, v70, 0x3fb8aa3b, v25
	v_exp_f32_e32 v69, v28
	v_add_f32_e32 v27, v56, v27
	v_mul_f32_e32 v24, 0x3fb8aa3b, v24
	v_add_f32_e32 v27, v56, v27
	v_exp_f32_e32 v70, v26
	v_fmac_f32_e32 v25, 0x3fb8aa3b, v71
	v_add_f32_e32 v27, v56, v27
	v_exp_f32_e32 v71, v25
	v_exp_f32_e32 v24, v24
	v_add_f32_e32 v27, v68, v27
	v_add_f32_e32 v25, v69, v27
	v_add_f32_e32 v25, v70, v25
	v_add_f32_e32 v200, v71, v25
	v_mul_f32_e32 v64, 0, v24
	v_cvt_pk_bf16_f32 v88, v56, v56
	v_fmac_f32_e32 v200, 0, v24
	v_mov_b32_e32 v65, v64
	v_mov_b32_e32 v66, v64
	v_mov_b32_e32 v67, v64
	v_mov_b32_e32 v89, v88
	v_mov_b32_e32 v90, v88
	v_mov_b32_e32 v91, v88
	v_cvt_pk_bf16_f32 v102, v68, v69
	v_cvt_pk_bf16_f32 v103, v70, v71
	v_mov_b32_e32 v57, v56
	v_mov_b32_e32 v58, v56
	v_mov_b32_e32 v59, v56
	v_mov_b32_e32 v60, v56
	v_mov_b32_e32 v61, v56
	v_mov_b32_e32 v62, v56
	v_mov_b32_e32 v63, v56
	v_mov_b32_e32 v44, v56
	v_mov_b32_e32 v45, v56
	v_mov_b32_e32 v46, v56
	v_mov_b32_e32 v47, v56
	v_mov_b32_e32 v40, v56
	v_mov_b32_e32 v41, v56
	v_mov_b32_e32 v42, v56
	v_mov_b32_e32 v43, v56
	v_mov_b32_e32 v36, v56
	v_mov_b32_e32 v37, v56
	v_mov_b32_e32 v38, v56
	v_mov_b32_e32 v39, v56
	v_mov_b32_e32 v28, v56
	v_mov_b32_e32 v29, v56
	v_mov_b32_e32 v30, v56
	v_mov_b32_e32 v31, v56
	v_mov_b32_e32 v24, v56
	v_mov_b32_e32 v25, v56
	v_mov_b32_e32 v26, v56
	v_mov_b32_e32 v27, v56
	v_mov_b32_e32 v100, v88
	s_branch .LBB0_201

.LBB0_279:
	v_max_f32_e32 v32, v142, v143
	v_max_f32_e32 v34, v138, v139
	v_max3_f32 v32, v140, v141, v32
	v_max3_f32 v34, v136, v137, v34
	s_mov_b32 s20, 0xf149f2ca
	v_max3_f32 v32, v32, s20, v34
	v_max_f32_e32 v34, v134, v135
	v_max_f32_e32 v35, v130, v131
	v_max3_f32 v34, v132, v133, v34
	v_max3_f32 v35, v128, v129, v35
	v_max3_f32 v32, v32, v34, v35
	v_max_f32_e32 v34, v126, v127
	v_max_f32_e32 v35, v122, v123
	v_max3_f32 v34, v124, v125, v34
	v_max3_f32 v35, v120, v121, v35
	v_max3_f32 v32, v32, v34, v35
	v_max_f32_e32 v34, v86, v87
	v_max_f32_e32 v35, v114, v115
	v_max3_f32 v34, v84, v85, v34
	v_max3_f32 v35, v112, v113, v35
	v_max3_f32 v32, v32, v34, v35
	ds_bpermute_b32 v34, v198, v32
	s_waitcnt lgkmcnt(0)
	v_max_f32_e32 v34, v34, v34
	v_max_f32_e32 v32, v32, v34
	ds_bpermute_b32 v34, v199, v32
	s_waitcnt lgkmcnt(0)
	v_max3_f32 v34, v223, v32, v34
	v_mul_f32_e32 v32, 0xbfb8aa3b, v34
	v_fmamk_f32 v35, v140, 0x3fb8aa3b, v32
	v_exp_f32_e32 v140, v35
	v_fmamk_f32 v117, v141, 0x3fb8aa3b, v32
	v_exp_f32_e32 v141, v117
	v_fmamk_f32 v117, v142, 0x3fb8aa3b, v32
	v_exp_f32_e32 v142, v117
	v_fmamk_f32 v117, v143, 0x3fb8aa3b, v32
	v_exp_f32_e32 v143, v117
	v_fmamk_f32 v117, v136, 0x3fb8aa3b, v32
	v_add_f32_e32 v116, 0, v140
	v_exp_f32_e32 v136, v117
	v_fmamk_f32 v117, v137, 0x3fb8aa3b, v32
	v_add_f32_e32 v116, v141, v116
	v_exp_f32_e32 v137, v117
	v_fmamk_f32 v117, v138, 0x3fb8aa3b, v32
	v_add_f32_e32 v116, v142, v116
	v_exp_f32_e32 v138, v117
	v_fmamk_f32 v117, v139, 0x3fb8aa3b, v32
	v_add_f32_e32 v116, v143, v116
	v_exp_f32_e32 v139, v117
	v_fmamk_f32 v117, v132, 0x3fb8aa3b, v32
	v_add_f32_e32 v116, v136, v116
	v_exp_f32_e32 v132, v117
	v_fmamk_f32 v117, v133, 0x3fb8aa3b, v32
	v_add_f32_e32 v116, v137, v116
	v_exp_f32_e32 v133, v117
	v_fmamk_f32 v117, v134, 0x3fb8aa3b, v32
	v_add_f32_e32 v116, v138, v116
	v_exp_f32_e32 v134, v117
	v_fmamk_f32 v117, v135, 0x3fb8aa3b, v32
	v_add_f32_e32 v116, v139, v116
	v_exp_f32_e32 v135, v117
	v_fmamk_f32 v117, v128, 0x3fb8aa3b, v32
	v_add_f32_e32 v116, v132, v116
	v_exp_f32_e32 v128, v117
	v_fmamk_f32 v117, v129, 0x3fb8aa3b, v32
	v_add_f32_e32 v116, v133, v116
	v_exp_f32_e32 v129, v117
	v_fmamk_f32 v117, v130, 0x3fb8aa3b, v32
	v_add_f32_e32 v116, v134, v116
	v_exp_f32_e32 v130, v117
	v_fmamk_f32 v117, v131, 0x3fb8aa3b, v32
	v_add_f32_e32 v116, v135, v116
	v_exp_f32_e32 v131, v117
	v_fmamk_f32 v117, v124, 0x3fb8aa3b, v32
	v_add_f32_e32 v116, v128, v116
	v_exp_f32_e32 v124, v117
	v_fmamk_f32 v117, v125, 0x3fb8aa3b, v32
	v_add_f32_e32 v116, v129, v116
	v_exp_f32_e32 v125, v117
	v_fmamk_f32 v117, v126, 0x3fb8aa3b, v32
	v_add_f32_e32 v116, v130, v116
	v_exp_f32_e32 v126, v117
	v_fmamk_f32 v117, v127, 0x3fb8aa3b, v32
	v_add_f32_e32 v116, v131, v116
	v_exp_f32_e32 v127, v117
	v_fmamk_f32 v117, v120, 0x3fb8aa3b, v32
	v_add_f32_e32 v116, v124, v116
	v_exp_f32_e32 v120, v117
	v_fmamk_f32 v117, v121, 0x3fb8aa3b, v32
	v_add_f32_e32 v116, v125, v116
	v_exp_f32_e32 v121, v117
	v_fmamk_f32 v117, v122, 0x3fb8aa3b, v32
	v_add_f32_e32 v116, v126, v116
	v_exp_f32_e32 v122, v117
	v_fmamk_f32 v117, v123, 0x3fb8aa3b, v32
	v_add_f32_e32 v116, v127, v116
	v_exp_f32_e32 v123, v117
	v_fmamk_f32 v84, v84, 0x3fb8aa3b, v32
	v_add_f32_e32 v116, v120, v116
	v_exp_f32_e32 v84, v84
	v_fmamk_f32 v85, v85, 0x3fb8aa3b, v32
	v_add_f32_e32 v116, v121, v116
	v_exp_f32_e32 v85, v85
	v_fmamk_f32 v86, v86, 0x3fb8aa3b, v32
	v_add_f32_e32 v116, v122, v116
	v_exp_f32_e32 v86, v86
	v_fmamk_f32 v87, v87, 0x3fb8aa3b, v32
	v_add_f32_e32 v116, v123, v116
	v_exp_f32_e32 v87, v87
	v_fmamk_f32 v112, v112, 0x3fb8aa3b, v32
	v_add_f32_e32 v116, v84, v116
	v_exp_f32_e32 v112, v112
	v_fmamk_f32 v113, v113, 0x3fb8aa3b, v32
	v_add_f32_e32 v116, v85, v116
	v_exp_f32_e32 v113, v113
	v_fmamk_f32 v114, v114, 0x3fb8aa3b, v32
	v_sub_f32_e32 v35, v223, v34
	v_add_f32_e32 v116, v86, v116
	v_exp_f32_e32 v114, v114
	v_fmac_f32_e32 v32, 0x3fb8aa3b, v115
	v_mul_f32_e32 v35, 0x3fb8aa3b, v35
	v_add_f32_e32 v116, v87, v116
	v_exp_f32_e32 v115, v32
	v_add_f32_e32 v116, v112, v116
	v_exp_f32_e32 v32, v35
	v_add_f32_e32 v35, v113, v116
	v_add_f32_e32 v35, v114, v35
	v_add_f32_e32 v35, v115, v35
	v_fmac_f32_e32 v35, v195, v32
	v_pk_mul_f32 v[94:95], v[94:95], v[32:33] op_sel_hi:[1,0]
	v_pk_mul_f32 v[92:93], v[92:93], v[32:33] op_sel_hi:[1,0]
	v_pk_mul_f32 v[98:99], v[98:99], v[32:33] op_sel_hi:[1,0]
	v_pk_mul_f32 v[96:97], v[96:97], v[32:33] op_sel_hi:[1,0]
	v_pk_mul_f32 v[106:107], v[106:107], v[32:33] op_sel_hi:[1,0]
	v_pk_mul_f32 v[104:105], v[104:105], v[32:33] op_sel_hi:[1,0]
	v_pk_mul_f32 v[110:111], v[110:111], v[32:33] op_sel_hi:[1,0]
	v_pk_mul_f32 v[108:109], v[108:109], v[32:33] op_sel_hi:[1,0]
	v_cvt_pk_bf16_f32 v152, v140, v141
	v_cvt_pk_bf16_f32 v153, v142, v143
	v_cvt_pk_bf16_f32 v154, v136, v137
	v_cvt_pk_bf16_f32 v155, v138, v139
	v_cvt_pk_bf16_f32 v156, v132, v133
	v_cvt_pk_bf16_f32 v157, v134, v135
	v_cvt_pk_bf16_f32 v158, v128, v129
	v_cvt_pk_bf16_f32 v159, v130, v131
	v_cvt_pk_bf16_f32 v160, v124, v125
	v_cvt_pk_bf16_f32 v161, v126, v127
	v_cvt_pk_bf16_f32 v162, v120, v121
	v_cvt_pk_bf16_f32 v163, v122, v123
	v_cvt_pk_bf16_f32 v116, v84, v85
	v_cvt_pk_bf16_f32 v117, v86, v87
	v_cvt_pk_bf16_f32 v118, v112, v113
	v_cvt_pk_bf16_f32 v119, v114, v115
	v_mov_b32_e32 v195, v35
	v_mov_b32_e32 v223, v34
	s_and_b64 vcc, exec, s[18:19]
	s_cbranch_vccz .LBB0_316

.LBB0_318:
	v_max_f32_e32 v32, v26, v27
	v_max_f32_e32 v34, v30, v31
	v_max3_f32 v32, v24, v25, v32
	v_max3_f32 v34, v28, v29, v34
	s_mov_b32 s20, 0xf149f2ca
	v_max3_f32 v32, v32, s20, v34
	v_max_f32_e32 v34, v38, v39
	v_max_f32_e32 v35, v42, v43
	v_max3_f32 v34, v36, v37, v34
	v_max3_f32 v35, v40, v41, v35
	v_max3_f32 v32, v32, v34, v35
	v_max_f32_e32 v34, v46, v47
	v_max_f32_e32 v35, v62, v63
	v_max3_f32 v34, v44, v45, v34
	v_max3_f32 v35, v60, v61, v35
	v_max3_f32 v32, v32, v34, v35
	v_max_f32_e32 v34, v58, v59
	v_max_f32_e32 v35, v70, v71
	v_max3_f32 v34, v56, v57, v34
	v_max3_f32 v35, v68, v69, v35
	v_max3_f32 v32, v32, v34, v35
	ds_bpermute_b32 v34, v198, v32
	s_waitcnt lgkmcnt(0)
	v_max_f32_e32 v34, v34, v34
	v_max_f32_e32 v32, v32, v34
	ds_bpermute_b32 v34, v199, v32
	s_waitcnt lgkmcnt(0)
	v_max3_f32 v34, v201, v32, v34
	v_mul_f32_e32 v32, 0xbfb8aa3b, v34
	v_fmamk_f32 v24, v24, 0x3fb8aa3b, v32
	v_exp_f32_e32 v24, v24
	v_fmamk_f32 v25, v25, 0x3fb8aa3b, v32
	v_exp_f32_e32 v25, v25
	v_fmamk_f32 v26, v26, 0x3fb8aa3b, v32
	v_exp_f32_e32 v26, v26
	v_fmamk_f32 v27, v27, 0x3fb8aa3b, v32
	v_exp_f32_e32 v27, v27
	v_fmamk_f32 v28, v28, 0x3fb8aa3b, v32
	v_add_f32_e32 v88, 0, v24
	v_exp_f32_e32 v28, v28
	v_fmamk_f32 v29, v29, 0x3fb8aa3b, v32
	v_add_f32_e32 v88, v25, v88
	v_exp_f32_e32 v29, v29
	v_fmamk_f32 v30, v30, 0x3fb8aa3b, v32
	v_add_f32_e32 v88, v26, v88
	v_exp_f32_e32 v30, v30
	v_fmamk_f32 v31, v31, 0x3fb8aa3b, v32
	v_add_f32_e32 v88, v27, v88
	v_exp_f32_e32 v31, v31
	v_fmamk_f32 v36, v36, 0x3fb8aa3b, v32
	v_add_f32_e32 v88, v28, v88
	v_exp_f32_e32 v36, v36
	v_fmamk_f32 v37, v37, 0x3fb8aa3b, v32
	v_add_f32_e32 v88, v29, v88
	v_exp_f32_e32 v37, v37
	v_fmamk_f32 v38, v38, 0x3fb8aa3b, v32
	v_add_f32_e32 v88, v30, v88
	v_exp_f32_e32 v38, v38
	v_fmamk_f32 v39, v39, 0x3fb8aa3b, v32
	v_add_f32_e32 v88, v31, v88
	v_exp_f32_e32 v39, v39
	v_fmamk_f32 v40, v40, 0x3fb8aa3b, v32
	v_add_f32_e32 v88, v36, v88
	v_exp_f32_e32 v40, v40
	v_fmamk_f32 v41, v41, 0x3fb8aa3b, v32
	v_add_f32_e32 v88, v37, v88
	v_exp_f32_e32 v41, v41
	v_fmamk_f32 v42, v42, 0x3fb8aa3b, v32
	v_add_f32_e32 v88, v38, v88
	v_exp_f32_e32 v42, v42
	v_fmamk_f32 v43, v43, 0x3fb8aa3b, v32
	v_add_f32_e32 v88, v39, v88
	v_exp_f32_e32 v43, v43
	v_fmamk_f32 v44, v44, 0x3fb8aa3b, v32
	v_add_f32_e32 v88, v40, v88
	v_exp_f32_e32 v44, v44
	v_fmamk_f32 v45, v45, 0x3fb8aa3b, v32
	v_add_f32_e32 v88, v41, v88
	v_exp_f32_e32 v45, v45
	v_fmamk_f32 v46, v46, 0x3fb8aa3b, v32
	v_add_f32_e32 v88, v42, v88
	v_exp_f32_e32 v46, v46
	v_fmamk_f32 v47, v47, 0x3fb8aa3b, v32
	v_add_f32_e32 v88, v43, v88
	v_exp_f32_e32 v47, v47
	v_fmamk_f32 v60, v60, 0x3fb8aa3b, v32
	v_add_f32_e32 v88, v44, v88
	v_exp_f32_e32 v60, v60
	v_fmamk_f32 v61, v61, 0x3fb8aa3b, v32
	v_add_f32_e32 v88, v45, v88
	v_exp_f32_e32 v61, v61
	v_fmamk_f32 v62, v62, 0x3fb8aa3b, v32
	v_add_f32_e32 v88, v46, v88
	v_exp_f32_e32 v62, v62
	v_fmamk_f32 v63, v63, 0x3fb8aa3b, v32
	v_add_f32_e32 v88, v47, v88
	v_exp_f32_e32 v63, v63
	v_fmamk_f32 v56, v56, 0x3fb8aa3b, v32
	v_add_f32_e32 v88, v60, v88
	v_exp_f32_e32 v56, v56
	v_fmamk_f32 v57, v57, 0x3fb8aa3b, v32
	v_add_f32_e32 v88, v61, v88
	v_exp_f32_e32 v57, v57
	v_fmamk_f32 v58, v58, 0x3fb8aa3b, v32
	v_add_f32_e32 v88, v62, v88
	v_exp_f32_e32 v58, v58
	v_fmamk_f32 v59, v59, 0x3fb8aa3b, v32
	v_add_f32_e32 v88, v63, v88
	v_exp_f32_e32 v59, v59
	v_fmamk_f32 v68, v68, 0x3fb8aa3b, v32
	v_add_f32_e32 v88, v56, v88
	v_exp_f32_e32 v68, v68
	v_fmamk_f32 v69, v69, 0x3fb8aa3b, v32
	v_add_f32_e32 v88, v57, v88
	v_exp_f32_e32 v69, v69
	v_fmamk_f32 v70, v70, 0x3fb8aa3b, v32
	v_sub_f32_e32 v35, v201, v34
	v_add_f32_e32 v88, v58, v88
	v_exp_f32_e32 v70, v70
	v_fmac_f32_e32 v32, 0x3fb8aa3b, v71
	v_mul_f32_e32 v35, 0x3fb8aa3b, v35
	v_add_f32_e32 v88, v59, v88
	v_exp_f32_e32 v71, v32
	v_add_f32_e32 v88, v68, v88
	v_exp_f32_e32 v32, v35
	v_add_f32_e32 v35, v69, v88
	v_add_f32_e32 v35, v70, v35
	v_add_f32_e32 v35, v71, v35
	v_fmac_f32_e32 v35, v200, v32
	v_pk_mul_f32 v[74:75], v[74:75], v[32:33] op_sel_hi:[1,0]
	v_pk_mul_f32 v[72:73], v[72:73], v[32:33] op_sel_hi:[1,0]
	v_pk_mul_f32 v[78:79], v[78:79], v[32:33] op_sel_hi:[1,0]
	v_pk_mul_f32 v[76:77], v[76:77], v[32:33] op_sel_hi:[1,0]
	v_pk_mul_f32 v[82:83], v[82:83], v[32:33] op_sel_hi:[1,0]
	v_pk_mul_f32 v[80:81], v[80:81], v[32:33] op_sel_hi:[1,0]
	v_pk_mul_f32 v[66:67], v[66:67], v[32:33] op_sel_hi:[1,0]
	v_pk_mul_f32 v[64:65], v[64:65], v[32:33] op_sel_hi:[1,0]
	v_cvt_pk_bf16_f32 v144, v24, v25
	v_cvt_pk_bf16_f32 v145, v26, v27
	v_cvt_pk_bf16_f32 v146, v28, v29
	v_cvt_pk_bf16_f32 v147, v30, v31
	v_cvt_pk_bf16_f32 v148, v36, v37
	v_cvt_pk_bf16_f32 v149, v38, v39
	v_cvt_pk_bf16_f32 v150, v40, v41
	v_cvt_pk_bf16_f32 v151, v42, v43
	v_cvt_pk_bf16_f32 v88, v44, v45
	v_cvt_pk_bf16_f32 v89, v46, v47
	v_cvt_pk_bf16_f32 v90, v60, v61
	v_cvt_pk_bf16_f32 v91, v62, v63
	v_cvt_pk_bf16_f32 v100, v56, v57
	v_cvt_pk_bf16_f32 v101, v58, v59
	v_cvt_pk_bf16_f32 v102, v68, v69
	v_cvt_pk_bf16_f32 v103, v70, v71
	v_mov_b32_e32 v200, v35
	v_mov_b32_e32 v201, v34
	s_and_b64 vcc, exec, s[96:97]
	s_cbranch_vccz .Lpv_fast
	ds_read_b64 v[164:165], v202 offset:18432
	ds_read_b64 v[166:167], v203 offset:18432
	s_and_b64 vcc, exec, s[96:97]
	s_cbranch_vccz .LBB0_281
